# preadd loop: mid-element load issued together with the row loads (one round trip per row instead of two)
# speedup vs baseline: 1.0062x; 1.0032x over previous
.LBB0_261:
	s_or_b64 exec, exec, s[30:31]
	s_waitcnt vmcnt(0)
	v_and_b32_e32 v19, 0xffff0000, v9
	v_lshlrev_b32_e32 v20, 16, v2
	v_and_b32_e32 v21, 0xffff0000, v2
	v_pk_fma_f32 v[18:19], v[10:11], v[18:19], v[20:21]
	v_lshlrev_b32_e32 v21, 16, v9
	v_and_b32_e32 v23, s0, v9
	v_and_b32_e32 v22, 0xffff0000, v8
	v_lshlrev_b32_e32 v2, 16, v3
	v_and_b32_e32 v3, 0xffff0000, v3
	v_pk_mov_b32 v[20:21], v[20:21], v[22:23] op_sel:[1,0]
	v_lshlrev_b32_e32 v8, 16, v8
	v_pk_fma_f32 v[20:21], v[10:11], v[20:21], v[2:3]
	v_lshlrev_b32_e32 v2, 16, v4
	v_and_b32_e32 v3, 0xffff0000, v4
	v_and_b32_e32 v9, 0xffff0000, v7
	v_pk_fma_f32 v[8:9], v[10:11], v[8:9], v[2:3]
	v_lshlrev_b32_e32 v3, 16, v7
	v_and_b32_e32 v7, s0, v7
	v_and_b32_e32 v6, 0xffff0000, v6
	v_pk_mov_b32 v[2:3], v[2:3], v[6:7] op_sel:[1,0]
	v_lshlrev_b32_e32 v4, 16, v5
	v_and_b32_e32 v5, 0xffff0000, v5
	v_pk_fma_f32 v[6:7], v[10:11], v[2:3], v[4:5]
	s_lshl_b64 s[24:25], s[22:23], 13
	s_add_i32 s22, s22, s62
	v_cvt_pk_bf16_f32 v3, v20, v21
	v_cvt_pk_bf16_f32 v4, v8, v9
	v_cvt_pk_bf16_f32 v5, v6, v7
	v_lshl_add_u64 v[6:7], v[16:17], 0, s[24:25]
	s_cmpk_lt_i32 s22, 0x1000
	s_waitcnt vmcnt(0)
	v_lshlrev_b32_e32 v0, 16, v24
	v_cndmask_b32_e64 v0, v18, v0, s[0:1]
	v_cvt_pk_bf16_f32 v2, v0, v19
	global_store_dwordx4 v[6:7], v[2:5], off
	s_cbranch_scc0 .LBB0_264
.LBB0_262:
	s_ashr_i32 s23, s22, 31
	s_lshl_b64 s[24:25], s[22:23], 14
	s_add_u32 s26, s6, s24
	s_addc_u32 s27, s7, s25
	v_lshl_add_u64 v[2:3], v[14:15], 1, s[26:27]
	v_lshl_add_u64 v[20:21], v[12:13], 1, s[26:27]
	global_load_dwordx4 v[2:5], v[2:3], off nt
	s_nop 0
	global_load_dwordx4 v[6:9], v[20:21], off offset:-16 nt
	global_load_ushort v24, v229, s[26:27]
	v_mov_b32_e32 v18, 0
	s_and_saveexec_b64 s[30:31], vcc
	s_cbranch_execz .LBB0_261
	global_load_ushort v0, v[20:21], off
	s_waitcnt vmcnt(0)
	v_lshlrev_b32_e32 v18, 16, v0
	s_branch .LBB0_261
